# v20: v19 + L2 warm-up loads of the next GLA item's rows/state issued behind the current item's loads (M1, M3 GLA items, RG-LRU unit before first GLA item)
# baseline (speedup 1.0000x reference)
; DI UnitInfo decode_unit(int unit) {
;     UnitInfo u;
;     if (unit < NUNIT_P) { u.prompt = 1; u.b = unit / NCH; u.c = unit - u.b * NCH; u.s = 0; const int tau0 = u.c == 0 ? 0 : NMETA + 64 * (u.c - 1); u.nvalid = u.c == 0 ? NMETA : 64; u.row0 = u.b * LP + tau0; }
;     else { u.prompt = 0; u.s = unit - NUNIT_P; u.b = 0; u.c = 0; u.row0 = MP + LS * u.s; u.nvalid = LS; }
;     return u;
; template <bool FINAL>
; DI void gla_unit(KA a, int l, int item, LAS unsigned char* lds) {
;     ...
;     float bl[2][8];
;     {
;         float wg[2][16], bg[2];
; #pragma unroll
;         for (int hh = 0; hh < 2; ++hh) {
;             const float* wg2 = a->in[18] + (size_t)l * 16 * 256 + (2 * hp + hh) * 64 + dk;
; #pragma unroll
;             for (int e = 0; e < 16; ++e) wg[hh][e] = wg2[e * 256];
;             bg[hh] = a->in[19][l * 256 + (2 * hp + hh) * 64 + dk];
;         }
;         float run0 = 0.f, run1 = 0.f;
; #pragma unroll
;         for (int jj = 0; jj < 8; ++jj) {
;             const int t = 8 * tg + jj;
;             float ga = 0.f, gb = 0.f;
;             if (t < nvalid) {
;                 const u32x4* lp = (const u32x4*)(U + (size_t)(row0 + t) * UN + U_LR);
;                 float lr[16]; unpack8(lp[0], lr); unpack8(lp[1], lr + 8);
;                 float za = bg[0], zb = bg[1];
; #pragma unroll
;                 for (int e = 0; e < 16; ++e) { za += wg[0][e] * lr[e]; zb += wg[1][e] * lr[e]; }
;                 ga = (fminf(za, 0.f) - __logf(1.f + __expf(-fabsf(za)))) * (1.f / 16.f);
;                 gb = (fminf(zb, 0.f) - __logf(1.f + __expf(-fabsf(zb)))) * (1.f / 16.f);
;             }
;             run0 += ga; run1 += gb; bl[0][jj] = run0; bl[1][jj] = run1;
;         }
.LBB0_649:
	s_load_dwordx4 s[4:7], s[2:3], 0x90
	v_readlane_b32 s24, v255, 1
	v_readlane_b32 s25, v255, 2
	s_lshl_b64 s[24:25], s[24:25], 2
	v_lshlrev_b32_e32 v144, 2, v75
	s_waitcnt lgkmcnt(0)
	s_add_u32 s4, s4, s24
	s_addc_u32 s5, s5, s25
	v_readlane_b32 s0, v255, 3
	v_lshl_add_u64 v[16:17], s[4:5], 0, v[144:145]
	v_mov_b32_e32 v29, v145
	v_or_b32_e32 v44, s0, v75
	s_lshl_b32 s0, s60, 2
	v_lshl_add_u64 v[16:17], v[16:17], 0, s[0:1]
	s_movk_i32 s0, 0x1000
	v_add_co_u32_e32 v18, vcc, s0, v16
	s_movk_i32 s0, 0x2000
	s_nop 0
	v_addc_co_u32_e32 v19, vcc, 0, v17, vcc
	v_add_co_u32_e32 v20, vcc, s0, v16
	s_movk_i32 s0, 0x3000
	s_nop 0
	v_addc_co_u32_e32 v21, vcc, 0, v17, vcc
	v_add_co_u32_e32 v42, vcc, s0, v16
	v_or_b32_e32 v28, s60, v44
	s_nop 0
	v_addc_co_u32_e32 v43, vcc, 0, v17, vcc
	v_lshl_add_u64 v[28:29], v[28:29], 2, s[6:7]
	global_load_dword v112, v[16:17], off
	global_load_dword v111, v[16:17], off offset:1024
	global_load_dword v110, v[16:17], off offset:2048
	global_load_dword v109, v[16:17], off offset:3072
	global_load_dword v115, v[20:21], off offset:-4096
	global_load_dword v114, v[18:19], off offset:1024
	global_load_dword v33, v[18:19], off offset:2048
	global_load_dword v32, v[18:19], off offset:3072
	global_load_dword v31, v[20:21], off
	global_load_dword v30, v[20:21], off offset:1024
	global_load_dword v27, v[20:21], off offset:2048
	global_load_dword v26, v[20:21], off offset:3072
	global_load_dword v25, v[42:43], off
	global_load_dword v24, v[42:43], off offset:1024
	global_load_dword v23, v[42:43], off offset:2048
	global_load_dword v22, v[42:43], off offset:3072
	global_load_dword v113, v[28:29], off
	global_load_dword v118, v[16:17], off offset:256
	global_load_dword v117, v[16:17], off offset:1280
	global_load_dword v116, v[16:17], off offset:2304
	global_load_dword v121, v[16:17], off offset:3328
	global_load_dword v120, v[18:19], off offset:256
	global_load_dword v119, v[18:19], off offset:1280
	global_load_dword v41, v[18:19], off offset:2304
	global_load_dword v40, v[18:19], off offset:3328
	global_load_dword v39, v[20:21], off offset:256
	global_load_dword v38, v[20:21], off offset:1280
	global_load_dword v37, v[20:21], off offset:2304
	global_load_dword v36, v[20:21], off offset:3328
	global_load_dword v35, v[42:43], off offset:256
	global_load_dword v34, v[42:43], off offset:1280
	global_load_dword v29, v[42:43], off offset:2304
	global_load_dword v28, v[42:43], off offset:3328
	v_add_u32_e32 v16, s60, v44
	v_mov_b32_e32 v17, v145
	v_lshl_add_u64 v[16:17], v[16:17], 2, s[6:7]
	global_load_dword v122, v[16:17], off offset:256
	v_lshrrev_b32_e32 v128, 3, v75
	v_mul_u32_u24_e32 v128, 0x1600, v128
	v_and_b32_e32 v129, 7, v75
	v_lshl_add_u32 v128, v129, 2, v128
	s_add_i32 s72, s59, s51
	s_mul_hi_i32 s73, s72, 0x1600
	s_mulk_i32 s72, 0x1600
	s_add_u32 s72, s34, s72
	s_addc_u32 s73, s35, s73
	s_add_u32 s72, s72, 0x1400
	s_addc_u32 s73, s73, 0
	global_load_dword v129, v128, s[72:73]
	s_add_i32 s72, s33, 0x100
	s_cmpk_gt_i32 s72, 0x30f
	s_cbranch_scc1 .Lwm1_end
	s_lshr_b32 s73, s72, 1
	s_and_b32 s74, s72, 1
	s_cmpk_lt_u32 s73, 0x108
	s_cbranch_scc0 .Lwm1_samp
	s_mul_i32 s75, s73, 0xf83f
	s_lshr_b32 s75, s75, 21
	s_mul_i32 s76, s75, 0xffffffdf
	s_add_i32 s76, s76, s73
	s_lshl_b32 s77, s76, 6
	s_sub_i32 s77, s77, 48
	s_cmp_eq_u32 s76, 0
	s_cselect_b32 s77, 0, s77
	s_cselect_b32 s78, 15, 63
	s_cselect_b32 s79, 0, 1
	s_mulk_i32 s75, 0x810
	s_add_i32 s77, s77, s75
	s_branch .Lwm1_go
.Lwm1_samp:
	s_add_i32 s77, s73, 0xfffffef8
	s_lshl_b32 s77, s77, 3
	s_addk_i32 s77, 0x4080
	s_mov_b32 s78, 7
	s_mov_b32 s79, 0
.Lwm1_go:
	v_and_b32_e32 v130, 7, v75
	v_lshrrev_b32_e32 v131, 3, v75
	v_add_u32_e32 v131, s59, v131
	s_lshl_b32 s80, s74, 8
	s_lshl_b32 s81, s74, 9
	v_lshlrev_b32_e32 v132, 7, v130
	s_add_i32 s75, s80, 0xa00
	v_mov_b32_e32 v133, s75
	s_add_i32 s75, s81, 0xb00
	v_mov_b32_e32 v134, s75
	v_cmp_gt_u32_e32 vcc, 2, v130
	s_nop 1
	v_cndmask_b32_e32 v133, v134, v133, vcc
	v_add_u32_e32 v132, v132, v133
	v_mov_b32_e32 v134, 0x1400
	v_cmp_gt_u32_e32 vcc, 6, v130
	s_nop 1
	v_cndmask_b32_e32 v132, v134, v132, vcc
	v_min_u32_e32 v135, s78, v131
	v_add_u32_e32 v135, s77, v135
	v_mul_u32_u24_e32 v135, 0x1600, v135
	v_add_u32_e32 v135, v135, v132
	global_load_dword v136, v135, s[34:35]
.Lwm1_end:
	v_mov_b32_e32 v42, 0
	s_and_b64 vcc, exec, s[22:23]
	v_mov_b32_e32 v20, 0
	v_mov_b32_e32 v21, 0
	s_cbranch_vccnz .LBB0_651
	s_add_i32 s0, s59, s51
	s_mul_hi_i32 s5, s0, 0x1600
	s_mulk_i32 s0, 0x1600
	s_add_u32 s4, s34, s0
	s_addc_u32 s5, s35, s5
	s_add_u32 s6, s4, 0x1400
	s_addc_u32 s7, s5, 0
	s_mov_b32 s96, 0xbfb8aa3b
	s_mov_b32 s97, 0x3f317217
	s_waitcnt vmcnt(0)
	v_readlane_b32 s72, v129, 0
	v_readlane_b32 s73, v129, 1
	v_readlane_b32 s74, v129, 2
	v_readlane_b32 s75, v129, 3
	v_readlane_b32 s76, v129, 4
	v_readlane_b32 s77, v129, 5
	v_readlane_b32 s78, v129, 6
	v_readlane_b32 s79, v129, 7
	s_lshl_b32 s80, s72, 16
	s_and_b32 s81, s72, 0xffff0000
	s_lshl_b32 s82, s73, 16
	s_and_b32 s83, s73, 0xffff0000
	s_lshl_b32 s84, s74, 16
	s_and_b32 s85, s74, 0xffff0000
	s_lshl_b32 s86, s75, 16
	s_and_b32 s87, s75, 0xffff0000
	s_lshl_b32 s88, s76, 16
	s_and_b32 s89, s76, 0xffff0000
	s_lshl_b32 s90, s77, 16
	s_and_b32 s91, s77, 0xffff0000
	s_lshl_b32 s92, s78, 16
	s_and_b32 s93, s78, 0xffff0000
	s_lshl_b32 s94, s79, 16
	s_and_b32 s95, s79, 0xffff0000
	v_fma_f32 v16, v112, s80, v113
	v_fma_f32 v17, v118, s80, v122
	v_fmac_f32_e32 v16, s81, v111
	v_fmac_f32_e32 v17, s81, v117
	v_fmac_f32_e32 v16, s82, v110
	v_fmac_f32_e32 v17, s82, v116
	v_fmac_f32_e32 v16, s83, v109
	v_fmac_f32_e32 v17, s83, v121
	v_fmac_f32_e32 v16, s84, v115
	v_fmac_f32_e32 v17, s84, v120
	v_fmac_f32_e32 v16, s85, v114
	v_fmac_f32_e32 v17, s85, v119
	v_fmac_f32_e32 v16, s86, v33
	v_fmac_f32_e32 v17, s86, v41
	v_fmac_f32_e32 v16, s87, v32
	v_fmac_f32_e32 v17, s87, v40
	v_fmac_f32_e32 v16, s88, v31
	v_fmac_f32_e32 v17, s88, v39
	v_fmac_f32_e32 v16, s89, v30
	v_fmac_f32_e32 v17, s89, v38
	v_fmac_f32_e32 v16, s90, v27
	v_fmac_f32_e32 v17, s90, v37
	v_fmac_f32_e32 v16, s91, v26
	v_fmac_f32_e32 v17, s91, v36
	v_fmac_f32_e32 v16, s92, v25
	v_fmac_f32_e32 v17, s92, v35
	v_fmac_f32_e32 v16, s93, v24
	v_fmac_f32_e32 v17, s93, v34
	v_fmac_f32_e32 v16, s94, v23
	v_fmac_f32_e32 v17, s94, v29
	v_fmac_f32_e32 v16, s95, v22
	v_fmac_f32_e32 v17, s95, v28
	v_mul_f32_e64 v18, |v16|, s96
	v_mul_f32_e64 v19, |v17|, s96
	v_exp_f32_e32 v18, v18
	v_exp_f32_e32 v19, v19
	v_min_f32_e32 v16, 0, v16
	v_min_f32_e32 v17, 0, v17
	v_add_f32_e32 v18, 1.0, v18
	v_add_f32_e32 v19, 1.0, v19
	v_log_f32_e32 v18, v18
	v_log_f32_e32 v19, v19
	s_nop 0
	v_mul_f32_e32 v20, 0x3f317217, v18
	v_mul_f32_e32 v21, 0x3f317217, v19
	v_fma_f32 v20, v18, s97, -v20
	v_fma_f32 v21, v19, s97, -v21
	v_fmac_f32_e32 v20, 0x3377d1cf, v18
	v_fmac_f32_e32 v21, 0x3377d1cf, v19
	v_fmac_f32_e32 v20, 0x3f317217, v18
	v_fmac_f32_e32 v21, 0x3f317217, v19
	v_sub_f32_e32 v16, v16, v20
	v_sub_f32_e32 v17, v17, v21
	v_mul_f32_e32 v20, 0x3d800000, v16
	v_mul_f32_e32 v21, 0x3d800000, v17

; DI int crow(int reg, int h) { return (reg & 3) + 8 * (reg >> 2) + 4 * h; }
; DI UnitInfo decode_unit(int unit) {
;     UnitInfo u;
;     if (unit < NUNIT_P) { u.prompt = 1; u.b = unit / NCH; u.c = unit - u.b * NCH; u.s = 0; const int tau0 = u.c == 0 ? 0 : NMETA + 64 * (u.c - 1); u.nvalid = u.c == 0 ? NMETA : 64; u.row0 = u.b * LP + tau0; }
;     else { u.prompt = 0; u.s = unit - NUNIT_P; u.b = 0; u.c = 0; u.row0 = MP + LS * u.s; u.nvalid = LS; }
;     return u;
; template <bool FINAL>
; DI void gla_unit(KA a, int l, int item, LAS unsigned char* lds) {
;     ...
;     if (FINAL) {
; #pragma unroll
;         for (int q = 0; q < 4; ++q) gnv[q] = *(const f32x4*)(a->in[20] + l * DV + vdvc + 4 * q);
;     }
;     float s0v[2][16];
;     if (!FINAL && !u.prompt) {
; #pragma unroll
;         for (int hh = 0; hh < 2; ++hh)
; #pragma unroll
;             for (int i = 0; i < 16; ++i) s0v[hh][i] = __builtin_nontemporal_load(S0[hh] + (32 * (w >> 2) + crow(i, h)) * 128 + 32 * (w & 3) + r);
;     }
;     float bl[2][8];
;     {
;         float wg[2][16], bg[2];
; #pragma unroll
;         for (int hh = 0; hh < 2; ++hh) {
;             const float* wg2 = a->in[18] + (size_t)l * 16 * 256 + (2 * hp + hh) * 64 + dk;
; #pragma unroll
;             for (int e = 0; e < 16; ++e) wg[hh][e] = wg2[e * 256];
;             bg[hh] = a->in[19][l * 256 + (2 * hp + hh) * 64 + dk];
;         }
;         float run0 = 0.f, run1 = 0.f;
; #pragma unroll
;         for (int jj = 0; jj < 8; ++jj) {
;             const int t = 8 * tg + jj;
;             float ga = 0.f, gb = 0.f;
;             if (t < nvalid) {
;                 const u32x4* lp = (const u32x4*)(U + (size_t)(row0 + t) * UN + U_LR);
;                 float lr[16]; unpack8(lp[0], lr); unpack8(lp[1], lr + 8);
;                 float za = bg[0], zb = bg[1];
; #pragma unroll
;                 for (int e = 0; e < 16; ++e) { za += wg[0][e] * lr[e]; zb += wg[1][e] * lr[e]; }
;                 ga = (fminf(za, 0.f) - __logf(1.f + __expf(-fabsf(za)))) * (1.f / 16.f);
;                 gb = (fminf(zb, 0.f) - __logf(1.f + __expf(-fabsf(zb)))) * (1.f / 16.f);
;             }
;             run0 += ga; run1 += gb; bl[0][jj] = run0; bl[1][jj] = run1;
;         }
.LBB0_885:
	s_load_dwordx4 s[4:7], s[2:3], 0x90
	s_nop 0
	s_load_dwordx2 s[2:3], s[2:3], 0xa0
	s_lshl_b64 s[26:27], s[60:61], 2
	v_lshlrev_b32_e32 v124, 2, v167
	v_lshlrev_b32_e32 v80, 2, v85
	v_mov_b32_e32 v81, v145
	s_waitcnt lgkmcnt(0)
	s_add_u32 s2, s2, s26
	s_addc_u32 s3, s3, s27
	global_load_dwordx4 v[32:35], v124, s[2:3] offset:48
	global_load_dwordx4 v[52:55], v124, s[2:3] offset:32
	global_load_dwordx4 v[56:59], v124, s[2:3] offset:16
	global_load_dwordx4 v[60:63], v124, s[2:3]
	v_readlane_b32 s2, v255, 1
	v_readlane_b32 s3, v255, 2
	s_lshl_b64 s[2:3], s[2:3], 2
	s_add_u32 s2, s4, s2
	s_addc_u32 s3, s5, s3
	v_readlane_b32 s0, v255, 3
	v_lshl_add_u64 v[80:81], s[2:3], 0, v[80:81]
	v_mov_b32_e32 v95, v145
	v_or_b32_e32 v110, s0, v85
	s_lshl_b32 s0, s54, 2
	v_lshl_add_u64 v[80:81], v[80:81], 0, s[0:1]
	s_movk_i32 s0, 0x1000
	v_add_co_u32_e32 v82, vcc, s0, v80
	s_movk_i32 s0, 0x2000
	s_nop 0
	v_addc_co_u32_e32 v83, vcc, 0, v81, vcc
	v_add_co_u32_e32 v86, vcc, s0, v80
	s_movk_i32 s0, 0x3000
	s_nop 0
	v_addc_co_u32_e32 v87, vcc, 0, v81, vcc
	v_add_co_u32_e32 v108, vcc, s0, v80
	v_or_b32_e32 v94, s54, v110
	s_nop 0
	v_addc_co_u32_e32 v109, vcc, 0, v81, vcc
	v_lshl_add_u64 v[94:95], v[94:95], 2, s[6:7]
	global_load_dword v176, v[80:81], off
	global_load_dword v175, v[80:81], off offset:1024
	global_load_dword v174, v[80:81], off offset:2048
	global_load_dword v173, v[80:81], off offset:3072
	global_load_dword v179, v[86:87], off offset:-4096
	global_load_dword v178, v[82:83], off offset:1024
	global_load_dword v99, v[82:83], off offset:2048
	global_load_dword v98, v[82:83], off offset:3072
	global_load_dword v97, v[86:87], off
	global_load_dword v96, v[86:87], off offset:1024
	global_load_dword v93, v[86:87], off offset:2048
	global_load_dword v92, v[86:87], off offset:3072
	global_load_dword v91, v[108:109], off
	global_load_dword v90, v[108:109], off offset:1024
	global_load_dword v89, v[108:109], off offset:2048
	global_load_dword v88, v[108:109], off offset:3072
	global_load_dword v177, v[94:95], off
	global_load_dword v182, v[80:81], off offset:256
	global_load_dword v181, v[80:81], off offset:1280
	global_load_dword v180, v[80:81], off offset:2304
	global_load_dword v185, v[80:81], off offset:3328
	global_load_dword v184, v[82:83], off offset:256
	global_load_dword v183, v[82:83], off offset:1280
	global_load_dword v107, v[82:83], off offset:2304
	global_load_dword v106, v[82:83], off offset:3328
	global_load_dword v105, v[86:87], off offset:256
	global_load_dword v104, v[86:87], off offset:1280
	global_load_dword v103, v[86:87], off offset:2304
	global_load_dword v102, v[86:87], off offset:3328
	global_load_dword v101, v[108:109], off offset:256
	global_load_dword v100, v[108:109], off offset:1280
	global_load_dword v95, v[108:109], off offset:2304
	global_load_dword v94, v[108:109], off offset:3328
	v_add_u32_e32 v80, s54, v110
	v_mov_b32_e32 v81, v145
	v_lshl_add_u64 v[80:81], v[80:81], 2, s[6:7]
	global_load_dword v186, v[80:81], off offset:256
	v_lshrrev_b32_e32 v192, 3, v85
	v_mul_u32_u24_e32 v192, 0x1600, v192
	v_and_b32_e32 v193, 7, v85
	v_lshl_add_u32 v192, v193, 2, v192
	s_add_i32 s72, s53, s46
	s_mul_hi_i32 s73, s72, 0x1600
	s_mulk_i32 s72, 0x1600
	s_add_u32 s72, s30, s72
	s_addc_u32 s73, s31, s73
	s_add_u32 s72, s72, 0x1400
	s_addc_u32 s73, s73, 0
	global_load_dword v193, v192, s[72:73]
	v_readlane_b32 s82, v254, 0
	s_sub_i32 s72, s62, 0x188
	s_cmpk_lt_i32 s82, 8
	s_cbranch_scc1 .Lwm3_end
	s_cmpk_lt_i32 s82, 0x88
	s_cbranch_scc0 .Lwm3_c
	s_cmpk_lt_i32 s72, 0x88
	s_cbranch_scc1 .Lwm3_b128
	s_cmpk_lt_i32 s72, 0x108
	s_cbranch_scc0 .Lwm3_end
	s_cmpk_lt_i32 s82, 48
	s_cbranch_scc0 .Lwm3_end
.Lwm3_b128:
	s_addk_i32 s72, 0x80
	s_branch .Lwm3_dec
.Lwm3_c:
	s_sub_i32 s83, s72, 0x130
	s_cmpk_lt_i32 s83, 0x168
	s_cbranch_scc0 .Lwm3_end
	s_addk_i32 s72, 0x78
.Lwm3_dec:
	s_lshr_b32 s73, s72, 1
	s_and_b32 s74, s72, 1
	s_cmpk_lt_u32 s73, 0x108
	s_cbranch_scc0 .Lwm3_samp
	s_mul_i32 s75, s73, 0xf83f
	s_lshr_b32 s75, s75, 21
	s_mul_i32 s76, s75, 0xffffffdf
	s_add_i32 s76, s76, s73
	s_lshl_b32 s77, s76, 6
	s_sub_i32 s77, s77, 48
	s_cmp_eq_u32 s76, 0
	s_cselect_b32 s77, 0, s77
	s_cselect_b32 s78, 15, 63
	s_cselect_b32 s79, 0, 1
	s_mulk_i32 s75, 0x810
	s_add_i32 s77, s77, s75
	s_branch .Lwm3_go

; DI float bf2f(unsigned v) { return __uint_as_float(v << 16); }
; template <bool FINAL>
; DI void gla_unit(KA a, int l, int item, LAS unsigned char* lds) {
;     ...
;     for (int hh = 0; hh < 2; ++hh) {
;         const int hd = 2 * hp + hh;
; #pragma unroll
;         for (int jj = 0; jj < 8; ++jj) {
;             const int t = 8 * tg + jj; kraw[hh][jj] = 0u; qraw[hh][jj] = 0u;
;             if (t < nvalid) { kraw[hh][jj] = U[(size_t)(row0 + t) * UN + U_K + hd * 64 + dk]; if (FINAL) qraw[hh][jj] = U[(size_t)(row0 + t) * UN + U_Q + hd * 64 + dk]; }
;         }
;         v0[hh] = (u32x4){0u, 0u, 0u, 0u}; v1[hh] = v0[hh]; g0[hh] = v0[hh]; g1[hh] = v0[hh];
;         if (vj < nvalid) {
;             const u32x4* vp = (const u32x4*)(U + (size_t)(row0 + vj) * UN + U_V + hd * 128 + vdvc); v0[hh] = vp[0]; v1[hh] = vp[1];
;             if (FINAL) { const u32x4* gp = (const u32x4*)(U + (size_t)(row0 + vj) * UN + U_GO + hd * 128 + vdvc); g0[hh] = gp[0]; g1[hh] = gp[1]; }
;         }
;         S0[hh] = nullptr;
;         if (!u.prompt) S0[hh] = a->in[4] + (size_t)((l * NSB + u.s) * 4 + hd) * 8192;
;         if (FINAL) {
;             const bf16_t* Sb = (u.prompt && u.c > 0) ? (const bf16_t*)(a->ws + WS_SB) + (size_t)(unit * 4 + hd) * 8192 : nullptr;
; #pragma unroll
;             for (int it = 0; it < 4; ++it) {
;                 const int idx = it * 512 + tid; sv[hh][it] = (f32x4){0.f, 0.f, 0.f, 0.f};
;                 if (S0[hh]) sv[hh][it] = *(const f32x4*)(S0[hh] + (idx >> 5) * 128 + (idx & 31) * 4);
;                 else if (Sb) { const u32x2 v = *(const u32x2*)(Sb + (idx >> 5) * 128 + (idx & 31) * 4); sv[hh][it] = (f32x4){bf2f(v.x & 0xffffu), __uint_as_float(v.x & 0xffff0000u), bf2f(v.y & 0xffffu), __uint_as_float(v.y & 0xffff0000u)}; }
;             }
;         }
;     ...
;             if (t < nvalid) {
;                 const u32x4* lp = (const u32x4*)(U + (size_t)(row0 + t) * UN + U_LR);
;                 float lr[16]; unpack8(lp[0], lr); unpack8(lp[1], lr + 8);
;                 float za = bg[0], zb = bg[1];
; #pragma unroll
;                 for (int e = 0; e < 16; ++e) { za += wg[0][e] * lr[e]; zb += wg[1][e] * lr[e]; }
;                 ga = (fminf(za, 0.f) - __logf(1.f + __expf(-fabsf(za)))) * (1.f / 16.f);
;                 gb = (fminf(zb, 0.f) - __logf(1.f + __expf(-fabsf(zb)))) * (1.f / 16.f);
;             }
.Lwm3_go:
	v_and_b32_e32 v187, 15, v85
	v_lshrrev_b32_e32 v188, 4, v85
	v_add_u32_e32 v188, s53, v188
	s_lshl_b32 s80, s74, 8
	s_lshl_b32 s81, s74, 9
	v_lshlrev_b32_e32 v189, 7, v187
	s_add_i32 s75, s80, 0xa00
	v_mov_b32_e32 v190, s75
	s_add_i32 s75, s80, 0x700
	v_mov_b32_e32 v191, s75
	v_cmp_gt_u32_e32 vcc, 2, v187
	s_nop 1
	v_cndmask_b32_e32 v190, v191, v190, vcc
	s_add_i32 s75, s81, 0xa00
	v_mov_b32_e32 v191, s75
	v_cmp_gt_u32_e32 vcc, 4, v187
	s_nop 1
	v_cndmask_b32_e32 v190, v191, v190, vcc
	s_add_i32 s75, s81, 0xc00
	v_mov_b32_e32 v191, s75
	v_cmp_gt_u32_e32 vcc, 8, v187
	s_nop 1
	v_cndmask_b32_e32 v190, v191, v190, vcc
	v_add_u32_e32 v189, v189, v190
	v_mov_b32_e32 v191, 0x1400
	v_cmp_gt_u32_e32 vcc, 12, v187
	s_nop 1
	v_cndmask_b32_e32 v189, v191, v189, vcc
	v_min_u32_e32 v194, s78, v188
	v_add_u32_e32 v194, s77, v194
	v_mul_u32_u24_e32 v194, 0x1600, v194
	v_add_u32_e32 v194, v194, v189
	global_load_dword v195, v194, s[30:31]
	v_add_u32_e32 v188, 4, v188
	v_min_u32_e32 v194, s78, v188
	v_add_u32_e32 v194, s77, v194
	v_mul_u32_u24_e32 v194, 0x1600, v194
	v_add_u32_e32 v194, v194, v189
	global_load_dword v195, v194, s[30:31]
	s_cmp_eq_u32 s79, 0
	s_cbranch_scc1 .Lwm3_end
	s_lshl_b32 s75, s73, 2
	s_lshl_b32 s76, s74, 1
	s_add_i32 s75, s75, s76
	s_lshl_b32 s75, s75, 14
	s_add_i32 s75, s75, 0x8200000
	s_lshl_b32 s76, s53, 9
	s_add_i32 s75, s75, s76
	v_and_b32_e32 v194, 31, v85
	v_lshlrev_b32_e32 v194, 7, v194
	v_add_u32_e32 v194, s75, v194
	global_load_dword v195, v194, s[30:31]
.Lwm3_end:
	v_mov_b32_e32 v108, 0
	s_and_b64 vcc, exec, s[24:25]
	v_mov_b32_e32 v86, 0
	v_mov_b32_e32 v87, 0
	s_cbranch_vccnz .LBB0_887
	s_add_i32 s0, s53, s46
	s_mul_hi_i32 s3, s0, 0x1600
	s_mulk_i32 s0, 0x1600
	s_add_u32 s2, s30, s0
	s_addc_u32 s3, s31, s3
	s_add_u32 s4, s2, 0x1400
	s_addc_u32 s5, s3, 0
	s_mov_b32 s96, 0xbfb8aa3b
	s_mov_b32 s97, 0x3f317217
	s_waitcnt vmcnt(0)
	v_readlane_b32 s72, v193, 0
	v_readlane_b32 s73, v193, 1
	v_readlane_b32 s74, v193, 2
	v_readlane_b32 s75, v193, 3
	v_readlane_b32 s76, v193, 4
	v_readlane_b32 s77, v193, 5
	v_readlane_b32 s78, v193, 6
	v_readlane_b32 s79, v193, 7
	s_lshl_b32 s80, s72, 16
	s_and_b32 s81, s72, 0xffff0000
	s_lshl_b32 s82, s73, 16
	s_and_b32 s83, s73, 0xffff0000
	s_lshl_b32 s84, s74, 16
	s_and_b32 s85, s74, 0xffff0000
	s_lshl_b32 s86, s75, 16
	s_and_b32 s87, s75, 0xffff0000
	s_lshl_b32 s88, s76, 16
	s_and_b32 s89, s76, 0xffff0000
	s_lshl_b32 s90, s77, 16
	s_and_b32 s91, s77, 0xffff0000
	s_lshl_b32 s92, s78, 16
	s_and_b32 s93, s78, 0xffff0000
	s_lshl_b32 s94, s79, 16
	s_and_b32 s95, s79, 0xffff0000
	v_fma_f32 v80, v176, s80, v177
	v_fma_f32 v81, v182, s80, v186
	v_fmac_f32_e32 v80, s81, v175
	v_fmac_f32_e32 v81, s81, v181
	v_fmac_f32_e32 v80, s82, v174
	v_fmac_f32_e32 v81, s82, v180
	v_fmac_f32_e32 v80, s83, v173
	v_fmac_f32_e32 v81, s83, v185
	v_fmac_f32_e32 v80, s84, v179
	v_fmac_f32_e32 v81, s84, v184
	v_fmac_f32_e32 v80, s85, v178
	v_fmac_f32_e32 v81, s85, v183
	v_fmac_f32_e32 v80, s86, v99
	v_fmac_f32_e32 v81, s86, v107
	v_fmac_f32_e32 v80, s87, v98
	v_fmac_f32_e32 v81, s87, v106
	v_fmac_f32_e32 v80, s88, v97
	v_fmac_f32_e32 v81, s88, v105
	v_fmac_f32_e32 v80, s89, v96
	v_fmac_f32_e32 v81, s89, v104
	v_fmac_f32_e32 v80, s90, v93
	v_fmac_f32_e32 v81, s90, v103
	v_fmac_f32_e32 v80, s91, v92
	v_fmac_f32_e32 v81, s91, v102
	v_fmac_f32_e32 v80, s92, v91
	v_fmac_f32_e32 v81, s92, v101
	v_fmac_f32_e32 v80, s93, v90
	v_fmac_f32_e32 v81, s93, v100
	v_fmac_f32_e32 v80, s94, v89
	v_fmac_f32_e32 v81, s94, v95
	v_fmac_f32_e32 v80, s95, v88
	v_fmac_f32_e32 v81, s95, v94
	v_mul_f32_e64 v82, |v80|, s96
	v_mul_f32_e64 v83, |v81|, s96
	v_exp_f32_e32 v82, v82
	v_exp_f32_e32 v83, v83
	v_min_f32_e32 v80, 0, v80
	v_min_f32_e32 v81, 0, v81
	v_add_f32_e32 v82, 1.0, v82
	v_add_f32_e32 v83, 1.0, v83
	v_log_f32_e32 v82, v82
	v_log_f32_e32 v83, v83
	s_nop 0
	v_mul_f32_e32 v86, 0x3f317217, v82
	v_mul_f32_e32 v87, 0x3f317217, v83
	v_fma_f32 v86, v82, s97, -v86
	v_fma_f32 v87, v83, s97, -v87
	v_fmac_f32_e32 v86, 0x3377d1cf, v82
	v_fmac_f32_e32 v87, 0x3377d1cf, v83
	v_fmac_f32_e32 v86, 0x3f317217, v82
	v_fmac_f32_e32 v87, 0x3f317217, v83
	v_sub_f32_e32 v80, v80, v86
	v_sub_f32_e32 v81, v81, v87
	v_mul_f32_e32 v86, 0x3d800000, v80
	v_mul_f32_e32 v87, 0x3d800000, v81

; DI UnitInfo decode_unit(int unit) {
;     UnitInfo u;
;     if (unit < NUNIT_P) { u.prompt = 1; u.b = unit / NCH; u.c = unit - u.b * NCH; u.s = 0; const int tau0 = u.c == 0 ? 0 : NMETA + 64 * (u.c - 1); u.nvalid = u.c == 0 ? NMETA : 64; u.row0 = u.b * LP + tau0; }
;     else { u.prompt = 0; u.s = unit - NUNIT_P; u.b = 0; u.c = 0; u.row0 = MP + LS * u.s; u.nvalid = LS; }
;     return u;
.LBB0_958:
	s_or_b64 exec, exec, s[6:7]
	s_ashr_i32 s10, s8, 6
	v_readlane_b32 s82, v254, 0
	s_add_i32 s83, s62, 0x100
	s_cmp_eq_u32 s62, s82
	s_cselect_b32 s84, 1, 0
	s_cmpk_lt_i32 s83, 0x188
	s_cselect_b32 s85, 1, 0
	s_and_b32 s84, s84, s85
	s_cmp_lg_u32 s84, 0
	s_cbranch_scc1 .Lwlr_end
	s_cmpk_lt_i32 s82, 0x88
	s_cselect_b32 s83, 0, 0xa8
	s_add_i32 s72, s82, s83
	s_lshl_b32 s86, s10, 3
	v_and_b32_e32 v206, 63, v35
	s_lshr_b32 s73, s72, 1
	s_and_b32 s74, s72, 1
	s_cmpk_lt_u32 s73, 0x108
	s_cbranch_scc0 .Lwlr_samp
	s_mul_i32 s75, s73, 0xf83f
	s_lshr_b32 s75, s75, 21
	s_mul_i32 s76, s75, 0xffffffdf
	s_add_i32 s76, s76, s73
	s_lshl_b32 s77, s76, 6
	s_sub_i32 s77, s77, 48
	s_cmp_eq_u32 s76, 0
	s_cselect_b32 s77, 0, s77
	s_cselect_b32 s78, 15, 63
	s_cselect_b32 s79, 0, 1
	s_mulk_i32 s75, 0x810
	s_add_i32 s77, s77, s75
	s_branch .Lwlr_go

; template <bool FINAL>
; DI void lru_unit(KA a, int l, int unit, LAS unsigned char* lds) {
;     ...
;     {
;         const int tr = lane >> 3, cg8 = (lane & 7) * 8;
;         const bf16_t* src = U + (size_t)(row0 + tr) * UN + 64 * w + cg8;
;         u32x4 v[8];
; #pragma unroll
;         for (int k = 0; k < 8; ++k) { v[k] = (u32x4){0u, 0u, 0u, 0u}; if (8 * k + tr < nvalid) v[k] = *(const u32x4*)(src + (size_t)(8 * k) * UN); }
; #pragma unroll
;         for (int k = 0; k < 8; ++k) *(LAS u32x4*)(xr + (8 * k + tr) * 64 + cg8) = v[k];
;     }
;     {
;         const int ch = 64 * w + lane;
;         const float* cw = a->in[11] + (size_t)l * 4 * DLRU;
; template <bool FINAL>
; DI void gla_unit(KA a, int l, int item, LAS unsigned char* lds) {
;     ...
;     for (int hh = 0; hh < 2; ++hh) {
;         const int hd = 2 * hp + hh;
; #pragma unroll
;         for (int jj = 0; jj < 8; ++jj) {
;             const int t = 8 * tg + jj; kraw[hh][jj] = 0u; qraw[hh][jj] = 0u;
;             if (t < nvalid) { kraw[hh][jj] = U[(size_t)(row0 + t) * UN + U_K + hd * 64 + dk]; if (FINAL) qraw[hh][jj] = U[(size_t)(row0 + t) * UN + U_Q + hd * 64 + dk]; }
;         }
;         v0[hh] = (u32x4){0u, 0u, 0u, 0u}; v1[hh] = v0[hh]; g0[hh] = v0[hh]; g1[hh] = v0[hh];
;         if (vj < nvalid) {
;             const u32x4* vp = (const u32x4*)(U + (size_t)(row0 + vj) * UN + U_V + hd * 128 + vdvc); v0[hh] = vp[0]; v1[hh] = vp[1];
;             if (FINAL) { const u32x4* gp = (const u32x4*)(U + (size_t)(row0 + vj) * UN + U_GO + hd * 128 + vdvc); g0[hh] = gp[0]; g1[hh] = gp[1]; }
;         }
;         S0[hh] = nullptr;
;         if (!u.prompt) S0[hh] = a->in[4] + (size_t)((l * NSB + u.s) * 4 + hd) * 8192;
;         if (FINAL) {
;             const bf16_t* Sb = (u.prompt && u.c > 0) ? (const bf16_t*)(a->ws + WS_SB) + (size_t)(unit * 4 + hd) * 8192 : nullptr;
; #pragma unroll
;             for (int it = 0; it < 4; ++it) {
;                 const int idx = it * 512 + tid; sv[hh][it] = (f32x4){0.f, 0.f, 0.f, 0.f};
;                 if (S0[hh]) sv[hh][it] = *(const f32x4*)(S0[hh] + (idx >> 5) * 128 + (idx & 31) * 4);
;                 else if (Sb) { const u32x2 v = *(const u32x2*)(Sb + (idx >> 5) * 128 + (idx & 31) * 4); sv[hh][it] = (f32x4){bf2f(v.x & 0xffffu), __uint_as_float(v.x & 0xffff0000u), bf2f(v.y & 0xffffu), __uint_as_float(v.y & 0xffff0000u)}; }
;             }
;         }
.Lwlr_go:
	v_and_b32_e32 v199, 15, v206
	v_lshrrev_b32_e32 v200, 4, v206
	v_add_u32_e32 v200, s86, v200
	s_lshl_b32 s80, s74, 8
	s_lshl_b32 s81, s74, 9
	v_lshlrev_b32_e32 v201, 7, v199
	s_add_i32 s75, s80, 0xa00
	v_mov_b32_e32 v202, s75
	s_add_i32 s75, s80, 0x700
	v_mov_b32_e32 v203, s75
	v_cmp_gt_u32_e32 vcc, 2, v199
	s_nop 1
	v_cndmask_b32_e32 v202, v203, v202, vcc
	s_add_i32 s75, s81, 0xa00
	v_mov_b32_e32 v203, s75
	v_cmp_gt_u32_e32 vcc, 4, v199
	s_nop 1
	v_cndmask_b32_e32 v202, v203, v202, vcc
	s_add_i32 s75, s81, 0xc00
	v_mov_b32_e32 v203, s75
	v_cmp_gt_u32_e32 vcc, 8, v199
	s_nop 1
	v_cndmask_b32_e32 v202, v203, v202, vcc
	v_add_u32_e32 v201, v201, v202
	v_mov_b32_e32 v203, 0x1400
	v_cmp_gt_u32_e32 vcc, 12, v199
	s_nop 1
	v_cndmask_b32_e32 v201, v203, v201, vcc
	v_min_u32_e32 v204, s78, v200
	v_add_u32_e32 v204, s77, v204
	v_mul_u32_u24_e32 v204, 0x1600, v204
	v_add_u32_e32 v204, v204, v201
	global_load_dword v205, v204, s[4:5]
	v_add_u32_e32 v200, 4, v200
	v_min_u32_e32 v204, s78, v200
	v_add_u32_e32 v204, s77, v204
	v_mul_u32_u24_e32 v204, 0x1600, v204
	v_add_u32_e32 v204, v204, v201
	global_load_dword v205, v204, s[4:5]
	s_cmp_eq_u32 s79, 0
	s_cbranch_scc1 .Lwlr_end
	s_lshl_b32 s75, s73, 2
	s_lshl_b32 s76, s74, 1
	s_add_i32 s75, s75, s76
	s_lshl_b32 s75, s75, 14
	s_add_i32 s75, s75, 0x8200000
	s_lshl_b32 s76, s86, 9
	s_add_i32 s75, s75, s76
	v_and_b32_e32 v204, 31, v206
	v_lshlrev_b32_e32 v204, 7, v204
	v_add_u32_e32 v204, s75, v204
	global_load_dword v205, v204, s[4:5]
.Lwlr_end:
	s_lshl_b32 s6, s10, 13
	s_add_i32 s11, s6, 0
	s_add_i32 s22, s11, 0x12000
	v_lshlrev_b32_e32 v33, 7, v36
	v_add3_u32 v33, s22, v33, v144
	s_waitcnt vmcnt(0)
	ds_write_b128 v33, v[0:3]
	ds_write_b128 v33, v[8:11] offset:1024
	ds_write_b128 v33, v[4:7] offset:2048
	ds_write_b128 v33, v[16:19] offset:3072
	ds_write_b128 v33, v[12:15] offset:4096
	ds_write_b128 v33, v[24:27] offset:5120
	ds_write_b128 v33, v[20:23] offset:6144
	ds_write_b128 v33, v[28:31] offset:7168
	s_load_dwordx4 s[16:19], s[2:3], 0x58
	v_readlane_b32 s6, v255, 18
	v_and_b32_e32 v32, 63, v35
	v_readlane_b32 s7, v255, 19
	v_or_b32_e32 v4, s6, v32
	v_readlane_b32 s6, v255, 10
	v_readlane_b32 s7, v255, 11
	s_waitcnt lgkmcnt(0)
	s_add_u32 s6, s16, s6
	s_addc_u32 s7, s17, s7
	v_ashrrev_i32_e32 v5, 31, v4
	v_lshl_add_u64 v[2:3], v[4:5], 2, s[6:7]
	v_add_co_u32_e32 v8, vcc, 0x1000, v2
	v_readlane_b32 s6, v255, 0
	s_nop 0
	v_addc_co_u32_e32 v9, vcc, 0, v3, vcc
	global_load_dword v0, v[2:3], off
	global_load_dword v1, v[2:3], off offset:2048
	s_nop 0
	global_load_dword v2, v[8:9], off
	global_load_dword v3, v[8:9], off offset:2048
	v_add_u32_e32 v8, s6, v4
	v_mov_b32_e32 v6, s18
	v_mov_b32_e32 v7, s19
	v_ashrrev_i32_e32 v9, 31, v8
	v_lshl_add_u64 v[6:7], v[8:9], 2, v[6:7]
	global_load_dword v14, v[6:7], off
	v_readlane_b32 s6, v255, 16
	v_readlane_b32 s7, v255, 17
	s_mov_b64 s[8:9], -1
	s_and_b64 vcc, exec, s[6:7]
	s_cbranch_vccz .LBB0_960
	s_load_dwordx2 s[6:7], s[2:3], 0x18
	s_add_i32 s8, s0, s60
	s_mul_hi_u32 s9, s8, 0x1800
	s_mulk_i32 s8, 0x1800
	s_waitcnt lgkmcnt(0)
	s_add_u32 s6, s6, s8
	s_addc_u32 s7, s7, s9
	v_lshl_add_u64 v[8:9], v[4:5], 2, s[6:7]
	global_load_dword v6, v[8:9], off
	global_load_dword v7, v[8:9], off offset:2048
	v_add_co_u32_e32 v8, vcc, 0x1000, v8
	s_mov_b64 s[8:9], 0
	s_nop 0
	v_addc_co_u32_e32 v9, vcc, 0, v9, vcc
	global_load_dword v9, v[8:9], off
